# MLA tail also touches the next unit's first four K/V tiles (L2 warm-up)
# baseline (speedup 1.0000x reference)
.LBB0_1380:
	s_add_i32 s98, s37, 1
	s_lshl_b32 s98, s98, 3
	s_or_b32 s98, s98, s3
	s_mul_i32 s98, s98, s21
	s_add_i32 s98, s98, s20
	s_cmpk_gt_i32 s98, 0x3ff
	s_cbranch_scc1 .Lmla_warmna
	s_bfe_u32 s99, s98, 0x30003
	s_lshl_b32 s99, s99, 8
	s_ashr_i32 s100, s98, 6
	s_lshl_b32 s100, s100, 11
	v_lshrrev_b32_e32 v242, 1, v162
	v_add_u32_e32 v242, s100, v242
	v_lshlrev_b32_e32 v242, 11, v242
	v_and_b32_e32 v243, 1, v162
	v_lshl_add_u32 v243, v243, 7, s99
	v_add_u32_e32 v242, v242, v243
	v_mov_b32_e32 v243, 0
	v_lshl_add_u64 v[242:243], s[86:87], 0, v[242:243]
	global_load_dword v242, v[242:243], off
	s_bfe_u32 s99, s98, 0x30003
	s_mul_i32 s99, s99, 0xc0
	s_ashr_i32 s100, s98, 6
	s_lshl_b32 s100, s100, 11
	s_lshl_b32 s98, s98, 8
	s_and_b32 s98, s98, 0x700
	s_or_b32 s98, s100, s98
	v_lshrrev_b32_e32 v236, 1, v162
	v_add_u32_e32 v236, s98, v236
	v_and_b32_e32 v238, 1, v162
	v_lshlrev_b32_e32 v238, 7, v238
	v_add_u32_e32 v238, s99, v238
	v_mov_b32_e32 v239, 0
	v_mad_i64_i32 v[236:237], s[100:101], v236, s29, v[238:239]
	v_lshl_add_u64 v[236:237], s[18:19], 0, v[236:237]
	global_load_dword v240, v[236:237], off
	s_branch .Lmla_nowarm
